# G1 gate-tile stores: 64-bit VALU address add pairs replaced by scalar base + 32-bit lane offset (saddr form, 16 stores per gate tile); on top of the combined variant
# baseline (speedup 1.0000x reference)
.LBB0_342:
	s_cmp_gt_i32 s4, 17
	s_cselect_b64 s[2:3], -1, 0
	s_ashr_i32 s7, s6, 31
	s_ashr_i32 s5, s4, 31
	s_lshl_b64 s[14:15], s[4:5], 17
	s_lshl_b64 s[34:35], s[6:7], 22
	s_add_u32 s5, s62, s34
	s_addc_u32 s7, s63, s35
	s_add_u32 s14, s5, s14
	s_addc_u32 s15, s7, s15
	s_cmpk_eq_i32 s0, 0x200
	s_cselect_b64 s[40:41], -1, 0
	s_cmp_lt_i32 s4, 18
	s_mov_b32 s4, 0xffdc0000
	v_lshl_add_u64 v[150:151], v[134:135], 1, s[14:15]
	s_mov_b32 s5, -1
	v_lshl_add_u64 v[150:151], v[150:151], 0, s[4:5]
	v_cmp_eq_u64_e64 s[4:5], 0, v[154:155]
	s_mov_b64 s[42:43], -1
	s_cbranch_scc1 .LBB0_344
	v_readfirstlane_b32 s90, v150
	v_readfirstlane_b32 s91, v151
	s_nop 1
	v_subrev_u32_e32 v253, s90, v150
	v_mul_f32_e32 v164, 0xbfb8aa3b, v130
	v_exp_f32_e32 v164, v164
	v_mul_f32_e32 v165, 0xbfb8aa3b, v126
	v_exp_f32_e32 v165, v165
	v_mul_f32_e32 v167, 0xbfb8aa3b, v127
	v_add_f32_e32 v164, 1.0, v164
	v_min_f32_e32 v166, 0x7149f2ca, v164
	v_add_f32_e32 v164, 1.0, v165
	v_mul_f32_e32 v165, 0xbfb8aa3b, v131
	v_exp_f32_e32 v165, v165
	v_mul_f32_e32 v152, 0xbfb8aa3b, v128
	v_mul_f32_e32 v153, 0xbfb8aa3b, v124
	v_mul_f32_e32 v156, 0xbfb8aa3b, v129
	v_mul_f32_e32 v157, 0xbfb8aa3b, v125
	v_exp_f32_e32 v167, v167
	v_exp_f32_e32 v152, v152
	v_exp_f32_e32 v153, v153
	v_exp_f32_e32 v156, v156
	v_exp_f32_e32 v157, v157
	v_min_f32_e32 v168, 0x7149f2ca, v164
	v_add_f32_e32 v164, 1.0, v165
	v_min_f32_e32 v165, 0x7149f2ca, v164
	v_add_f32_e32 v164, 1.0, v167
	v_add_f32_e32 v152, 1.0, v152
	v_add_f32_e32 v153, 1.0, v153
	v_add_f32_e32 v156, 1.0, v156
	v_add_f32_e32 v157, 1.0, v157
	v_min_f32_e32 v167, 0x7149f2ca, v164
	s_mov_b64 s[42:43], 0
	v_min_f32_e32 v152, 0x7149f2ca, v152
	v_min_f32_e32 v153, 0x7149f2ca, v153
	v_min_f32_e32 v156, 0x7149f2ca, v156
	v_min_f32_e32 v157, 0x7149f2ca, v157
	v_cvt_pk_bf16_f32 v164, v152, v156
	v_cvt_pk_bf16_f32 v165, v166, v165
	v_cvt_pk_bf16_f32 v166, v153, v157
	v_cvt_pk_bf16_f32 v167, v168, v167
	global_store_dwordx4 v253, v[164:167], s[90:91] nt

.LBB0_348:
	v_cndmask_b32_e64 v124, 0, 1, s[2:3]
	v_cmp_ne_u32_e64 s[6:7], 1, v124
	s_andn2_b64 vcc, exec, s[2:3]
	s_mov_b64 s[2:3], -1
	s_cbranch_vccnz .LBB0_360
	v_mul_f32_e32 v125, 0xbfb8aa3b, v116
	v_exp_f32_e32 v125, v125
	v_mul_f32_e32 v126, 0xbfb8aa3b, v121
	v_mul_f32_e32 v127, 0xbfb8aa3b, v117
	v_exp_f32_e32 v126, v126
	v_exp_f32_e32 v127, v127
	v_mul_f32_e32 v124, 0xbfb8aa3b, v120
	v_add_f32_e32 v125, 1.0, v125
	v_exp_f32_e32 v124, v124
	v_min_f32_e32 v128, 0x7149f2ca, v125
	v_add_f32_e32 v125, 1.0, v126
	v_add_f32_e32 v126, 1.0, v127
	v_mul_f32_e32 v127, 0xbfb8aa3b, v122
	v_mul_f32_e32 v129, 0xbfb8aa3b, v118
	v_mul_f32_e32 v130, 0xbfb8aa3b, v123
	v_exp_f32_e32 v127, v127
	v_exp_f32_e32 v129, v129
	v_exp_f32_e32 v130, v130
	v_mul_f32_e32 v131, 0xbfb8aa3b, v119
	v_exp_f32_e32 v131, v131
	v_add_f32_e32 v124, 1.0, v124
	v_min_f32_e32 v124, 0x7149f2ca, v124
	v_min_f32_e32 v125, 0x7149f2ca, v125
	v_min_f32_e32 v126, 0x7149f2ca, v126
	v_add_f32_e32 v127, 1.0, v127
	v_add_f32_e32 v129, 1.0, v129
	v_add_f32_e32 v130, 1.0, v130
	v_min_f32_e32 v127, 0x7149f2ca, v127
	v_min_f32_e32 v129, 0x7149f2ca, v129
	v_min_f32_e32 v130, 0x7149f2ca, v130
	v_add_f32_e32 v131, 1.0, v131
	v_cvt_pk_bf16_f32 v124, v124, v125
	v_cvt_pk_bf16_f32 v125, v127, v130
	v_cvt_pk_bf16_f32 v126, v128, v126
	v_min_f32_e32 v131, 0x7149f2ca, v131
	v_cvt_pk_bf16_f32 v127, v129, v131
	s_nop 0
	s_add_u32 s88, s90, 0x2000
	s_addc_u32 s89, s91, 0
	global_store_dwordx4 v253, v[124:127], s[88:89] nt
	s_cbranch_execz .LBB0_361

.LBB0_351:
	v_mul_f32_e32 v117, 0xbfb8aa3b, v108
	v_exp_f32_e32 v117, v117
	v_mul_f32_e32 v118, 0xbfb8aa3b, v113
	v_mul_f32_e32 v119, 0xbfb8aa3b, v109
	v_exp_f32_e32 v118, v118
	v_exp_f32_e32 v119, v119
	v_mul_f32_e32 v116, 0xbfb8aa3b, v112
	v_add_f32_e32 v117, 1.0, v117
	v_exp_f32_e32 v116, v116
	v_min_f32_e32 v120, 0x7149f2ca, v117
	v_add_f32_e32 v117, 1.0, v118
	v_add_f32_e32 v118, 1.0, v119
	v_mul_f32_e32 v119, 0xbfb8aa3b, v114
	v_mul_f32_e32 v121, 0xbfb8aa3b, v110
	v_mul_f32_e32 v122, 0xbfb8aa3b, v115
	v_exp_f32_e32 v119, v119
	v_exp_f32_e32 v121, v121
	v_exp_f32_e32 v122, v122
	v_mul_f32_e32 v123, 0xbfb8aa3b, v111
	v_exp_f32_e32 v123, v123
	v_add_f32_e32 v116, 1.0, v116
	v_min_f32_e32 v116, 0x7149f2ca, v116
	v_min_f32_e32 v117, 0x7149f2ca, v117
	v_min_f32_e32 v118, 0x7149f2ca, v118
	v_add_f32_e32 v119, 1.0, v119
	v_add_f32_e32 v121, 1.0, v121
	v_add_f32_e32 v122, 1.0, v122
	v_min_f32_e32 v119, 0x7149f2ca, v119
	v_min_f32_e32 v121, 0x7149f2ca, v121
	v_min_f32_e32 v122, 0x7149f2ca, v122
	v_add_f32_e32 v123, 1.0, v123
	v_cvt_pk_bf16_f32 v116, v116, v117
	v_cvt_pk_bf16_f32 v117, v119, v122
	v_cvt_pk_bf16_f32 v118, v120, v118
	v_min_f32_e32 v123, 0x7149f2ca, v123
	v_cvt_pk_bf16_f32 v119, v121, v123
	s_nop 0
	s_mov_b64 s[2:3], 0
	s_add_u32 s88, s90, 0x4000
	s_addc_u32 s89, s91, 0
	global_store_dwordx4 v253, v[116:119], s[88:89] nt

.LBB0_365:
	v_mul_f32_e32 v109, 0xbfb8aa3b, v100
	v_exp_f32_e32 v109, v109
	v_mul_f32_e32 v110, 0xbfb8aa3b, v105
	v_mul_f32_e32 v111, 0xbfb8aa3b, v101
	v_exp_f32_e32 v110, v110
	v_exp_f32_e32 v111, v111
	v_mul_f32_e32 v108, 0xbfb8aa3b, v104
	v_add_f32_e32 v109, 1.0, v109
	v_exp_f32_e32 v108, v108
	v_min_f32_e32 v112, 0x7149f2ca, v109
	v_add_f32_e32 v109, 1.0, v110
	v_add_f32_e32 v110, 1.0, v111
	v_mul_f32_e32 v111, 0xbfb8aa3b, v106
	v_mul_f32_e32 v113, 0xbfb8aa3b, v102
	v_mul_f32_e32 v114, 0xbfb8aa3b, v107
	v_exp_f32_e32 v111, v111
	v_exp_f32_e32 v113, v113
	v_exp_f32_e32 v114, v114
	v_mul_f32_e32 v115, 0xbfb8aa3b, v103
	v_exp_f32_e32 v115, v115
	v_add_f32_e32 v108, 1.0, v108
	v_min_f32_e32 v108, 0x7149f2ca, v108
	v_min_f32_e32 v109, 0x7149f2ca, v109
	v_min_f32_e32 v110, 0x7149f2ca, v110
	v_add_f32_e32 v111, 1.0, v111
	v_add_f32_e32 v113, 1.0, v113
	v_add_f32_e32 v114, 1.0, v114
	v_min_f32_e32 v111, 0x7149f2ca, v111
	v_min_f32_e32 v113, 0x7149f2ca, v113
	v_min_f32_e32 v114, 0x7149f2ca, v114
	v_add_f32_e32 v115, 1.0, v115
	v_cvt_pk_bf16_f32 v108, v108, v109
	v_cvt_pk_bf16_f32 v109, v111, v114
	v_cvt_pk_bf16_f32 v110, v112, v110
	v_min_f32_e32 v115, 0x7149f2ca, v115
	v_cvt_pk_bf16_f32 v111, v113, v115
	s_nop 0
	s_add_u32 s88, s90, 0x6000
	s_addc_u32 s89, s91, 0
	global_store_dwordx4 v253, v[108:111], s[88:89] nt
	s_cbranch_execz .LBB0_357

.LBB0_367:
	v_mul_f32_e32 v101, 0xbfb8aa3b, v92
	v_exp_f32_e32 v101, v101
	v_mul_f32_e32 v102, 0xbfb8aa3b, v97
	v_mul_f32_e32 v103, 0xbfb8aa3b, v93
	v_exp_f32_e32 v102, v102
	v_exp_f32_e32 v103, v103
	v_mul_f32_e32 v100, 0xbfb8aa3b, v96
	v_add_f32_e32 v101, 1.0, v101
	v_exp_f32_e32 v100, v100
	v_min_f32_e32 v104, 0x7149f2ca, v101
	v_add_f32_e32 v101, 1.0, v102
	v_add_f32_e32 v102, 1.0, v103
	v_mul_f32_e32 v103, 0xbfb8aa3b, v98
	v_mul_f32_e32 v105, 0xbfb8aa3b, v94
	v_mul_f32_e32 v106, 0xbfb8aa3b, v99
	v_exp_f32_e32 v103, v103
	v_exp_f32_e32 v105, v105
	v_exp_f32_e32 v106, v106
	v_mul_f32_e32 v107, 0xbfb8aa3b, v95
	v_exp_f32_e32 v107, v107
	v_add_f32_e32 v100, 1.0, v100
	v_min_f32_e32 v100, 0x7149f2ca, v100
	v_min_f32_e32 v101, 0x7149f2ca, v101
	v_min_f32_e32 v102, 0x7149f2ca, v102
	v_add_f32_e32 v103, 1.0, v103
	v_add_f32_e32 v105, 1.0, v105
	v_add_f32_e32 v106, 1.0, v106
	v_min_f32_e32 v103, 0x7149f2ca, v103
	v_min_f32_e32 v105, 0x7149f2ca, v105
	v_min_f32_e32 v106, 0x7149f2ca, v106
	v_add_f32_e32 v107, 1.0, v107
	v_cvt_pk_bf16_f32 v100, v100, v101
	v_cvt_pk_bf16_f32 v101, v103, v106
	v_cvt_pk_bf16_f32 v102, v104, v102
	v_min_f32_e32 v107, 0x7149f2ca, v107
	v_cvt_pk_bf16_f32 v103, v105, v107
	s_nop 0
	s_mov_b64 s[2:3], 0
	s_add_u32 s88, s90, 0x8000
	s_addc_u32 s89, s91, 0
	global_store_dwordx4 v253, v[100:103], s[88:89] nt

.LBB0_377:
	v_mul_f32_e32 v93, 0xbfb8aa3b, v84
	v_exp_f32_e32 v93, v93
	v_mul_f32_e32 v94, 0xbfb8aa3b, v89
	v_mul_f32_e32 v95, 0xbfb8aa3b, v85
	v_exp_f32_e32 v94, v94
	v_exp_f32_e32 v95, v95
	v_mul_f32_e32 v92, 0xbfb8aa3b, v88
	v_add_f32_e32 v93, 1.0, v93
	v_exp_f32_e32 v92, v92
	v_min_f32_e32 v96, 0x7149f2ca, v93
	v_add_f32_e32 v93, 1.0, v94
	v_add_f32_e32 v94, 1.0, v95
	v_mul_f32_e32 v95, 0xbfb8aa3b, v90
	v_mul_f32_e32 v97, 0xbfb8aa3b, v86
	v_mul_f32_e32 v98, 0xbfb8aa3b, v91
	v_exp_f32_e32 v95, v95
	v_exp_f32_e32 v97, v97
	v_exp_f32_e32 v98, v98
	v_mul_f32_e32 v99, 0xbfb8aa3b, v87
	v_exp_f32_e32 v99, v99
	v_add_f32_e32 v92, 1.0, v92
	v_min_f32_e32 v92, 0x7149f2ca, v92
	v_min_f32_e32 v93, 0x7149f2ca, v93
	v_min_f32_e32 v94, 0x7149f2ca, v94
	v_add_f32_e32 v95, 1.0, v95
	v_add_f32_e32 v97, 1.0, v97
	v_add_f32_e32 v98, 1.0, v98
	v_min_f32_e32 v95, 0x7149f2ca, v95
	v_min_f32_e32 v97, 0x7149f2ca, v97
	v_min_f32_e32 v98, 0x7149f2ca, v98
	v_add_f32_e32 v99, 1.0, v99
	v_cvt_pk_bf16_f32 v92, v92, v93
	v_cvt_pk_bf16_f32 v93, v95, v98
	v_cvt_pk_bf16_f32 v94, v96, v94
	v_min_f32_e32 v99, 0x7149f2ca, v99
	v_cvt_pk_bf16_f32 v95, v97, v99
	s_nop 0
	s_add_u32 s88, s90, 0xa000
	s_addc_u32 s89, s91, 0
	global_store_dwordx4 v253, v[92:95], s[88:89] nt
	s_cbranch_execz .LBB0_373

.LBB0_379:
	v_mul_f32_e32 v85, 0xbfb8aa3b, v76
	v_exp_f32_e32 v85, v85
	v_mul_f32_e32 v86, 0xbfb8aa3b, v81
	v_mul_f32_e32 v87, 0xbfb8aa3b, v77
	v_exp_f32_e32 v86, v86
	v_exp_f32_e32 v87, v87
	v_mul_f32_e32 v84, 0xbfb8aa3b, v80
	v_add_f32_e32 v85, 1.0, v85
	v_exp_f32_e32 v84, v84
	v_min_f32_e32 v88, 0x7149f2ca, v85
	v_add_f32_e32 v85, 1.0, v86
	v_add_f32_e32 v86, 1.0, v87
	v_mul_f32_e32 v87, 0xbfb8aa3b, v82
	v_mul_f32_e32 v89, 0xbfb8aa3b, v78
	v_mul_f32_e32 v90, 0xbfb8aa3b, v83
	v_exp_f32_e32 v87, v87
	v_exp_f32_e32 v89, v89
	v_exp_f32_e32 v90, v90
	v_mul_f32_e32 v91, 0xbfb8aa3b, v79
	v_exp_f32_e32 v91, v91
	v_add_f32_e32 v84, 1.0, v84
	v_min_f32_e32 v84, 0x7149f2ca, v84
	v_min_f32_e32 v85, 0x7149f2ca, v85
	v_min_f32_e32 v86, 0x7149f2ca, v86
	v_add_f32_e32 v87, 1.0, v87
	v_add_f32_e32 v89, 1.0, v89
	v_add_f32_e32 v90, 1.0, v90
	v_min_f32_e32 v87, 0x7149f2ca, v87
	v_min_f32_e32 v89, 0x7149f2ca, v89
	v_min_f32_e32 v90, 0x7149f2ca, v90
	v_add_f32_e32 v91, 1.0, v91
	v_cvt_pk_bf16_f32 v84, v84, v85
	v_cvt_pk_bf16_f32 v85, v87, v90
	v_cvt_pk_bf16_f32 v86, v88, v86
	v_min_f32_e32 v91, 0x7149f2ca, v91
	v_cvt_pk_bf16_f32 v87, v89, v91
	s_nop 0
	s_mov_b64 s[2:3], 0
	s_add_u32 s88, s90, 0xc000
	s_addc_u32 s89, s91, 0
	global_store_dwordx4 v253, v[84:87], s[88:89] nt

.LBB0_389:
	v_mul_f32_e32 v77, 0xbfb8aa3b, v68
	v_exp_f32_e32 v77, v77
	v_mul_f32_e32 v78, 0xbfb8aa3b, v73
	v_mul_f32_e32 v79, 0xbfb8aa3b, v69
	v_exp_f32_e32 v78, v78
	v_exp_f32_e32 v79, v79
	v_mul_f32_e32 v76, 0xbfb8aa3b, v72
	v_add_f32_e32 v77, 1.0, v77
	v_exp_f32_e32 v76, v76
	v_min_f32_e32 v80, 0x7149f2ca, v77
	v_add_f32_e32 v77, 1.0, v78
	v_add_f32_e32 v78, 1.0, v79
	v_mul_f32_e32 v79, 0xbfb8aa3b, v74
	v_mul_f32_e32 v81, 0xbfb8aa3b, v70
	v_mul_f32_e32 v82, 0xbfb8aa3b, v75
	v_exp_f32_e32 v79, v79
	v_exp_f32_e32 v81, v81
	v_exp_f32_e32 v82, v82
	v_mul_f32_e32 v83, 0xbfb8aa3b, v71
	v_exp_f32_e32 v83, v83
	v_add_f32_e32 v76, 1.0, v76
	v_min_f32_e32 v76, 0x7149f2ca, v76
	v_min_f32_e32 v77, 0x7149f2ca, v77
	v_min_f32_e32 v78, 0x7149f2ca, v78
	v_add_f32_e32 v79, 1.0, v79
	v_add_f32_e32 v81, 1.0, v81
	v_add_f32_e32 v82, 1.0, v82
	v_min_f32_e32 v79, 0x7149f2ca, v79
	v_min_f32_e32 v81, 0x7149f2ca, v81
	v_min_f32_e32 v82, 0x7149f2ca, v82
	v_add_f32_e32 v83, 1.0, v83
	v_cvt_pk_bf16_f32 v76, v76, v77
	v_cvt_pk_bf16_f32 v77, v79, v82
	v_cvt_pk_bf16_f32 v78, v80, v78
	v_min_f32_e32 v83, 0x7149f2ca, v83
	v_cvt_pk_bf16_f32 v79, v81, v83
	s_nop 0
	s_add_u32 s88, s90, 0xe000
	s_addc_u32 s89, s91, 0
	global_store_dwordx4 v253, v[76:79], s[88:89] nt
	s_cbranch_execz .LBB0_385

.LBB0_391:
	v_mul_f32_e32 v69, 0xbfb8aa3b, v60
	v_exp_f32_e32 v69, v69
	v_mul_f32_e32 v70, 0xbfb8aa3b, v65
	v_mul_f32_e32 v71, 0xbfb8aa3b, v61
	v_exp_f32_e32 v70, v70
	v_exp_f32_e32 v71, v71
	v_mul_f32_e32 v68, 0xbfb8aa3b, v64
	v_add_f32_e32 v69, 1.0, v69
	v_exp_f32_e32 v68, v68
	v_min_f32_e32 v72, 0x7149f2ca, v69
	v_add_f32_e32 v69, 1.0, v70
	v_add_f32_e32 v70, 1.0, v71
	v_mul_f32_e32 v71, 0xbfb8aa3b, v66
	v_mul_f32_e32 v73, 0xbfb8aa3b, v62
	v_mul_f32_e32 v74, 0xbfb8aa3b, v67
	v_exp_f32_e32 v71, v71
	v_exp_f32_e32 v73, v73
	v_exp_f32_e32 v74, v74
	v_mul_f32_e32 v75, 0xbfb8aa3b, v63
	v_exp_f32_e32 v75, v75
	v_add_f32_e32 v68, 1.0, v68
	v_min_f32_e32 v68, 0x7149f2ca, v68
	v_min_f32_e32 v69, 0x7149f2ca, v69
	v_min_f32_e32 v70, 0x7149f2ca, v70
	v_add_f32_e32 v71, 1.0, v71
	v_add_f32_e32 v73, 1.0, v73
	v_add_f32_e32 v74, 1.0, v74
	v_min_f32_e32 v71, 0x7149f2ca, v71
	v_min_f32_e32 v73, 0x7149f2ca, v73
	v_min_f32_e32 v74, 0x7149f2ca, v74
	v_add_f32_e32 v75, 1.0, v75
	v_cvt_pk_bf16_f32 v68, v68, v69
	v_cvt_pk_bf16_f32 v69, v71, v74
	v_cvt_pk_bf16_f32 v70, v72, v70
	v_min_f32_e32 v75, 0x7149f2ca, v75
	v_cvt_pk_bf16_f32 v71, v73, v75
	s_nop 0
	s_mov_b64 s[2:3], 0
	s_add_u32 s88, s90, 0x10000
	s_addc_u32 s89, s91, 0
	global_store_dwordx4 v253, v[68:71], s[88:89] nt

.LBB0_401:
	v_mul_f32_e32 v61, 0xbfb8aa3b, v52
	v_exp_f32_e32 v61, v61
	v_mul_f32_e32 v62, 0xbfb8aa3b, v57
	v_mul_f32_e32 v63, 0xbfb8aa3b, v53
	v_exp_f32_e32 v62, v62
	v_exp_f32_e32 v63, v63
	v_mul_f32_e32 v60, 0xbfb8aa3b, v56
	v_add_f32_e32 v61, 1.0, v61
	v_exp_f32_e32 v60, v60
	v_min_f32_e32 v64, 0x7149f2ca, v61
	v_add_f32_e32 v61, 1.0, v62
	v_add_f32_e32 v62, 1.0, v63
	v_mul_f32_e32 v63, 0xbfb8aa3b, v58
	v_mul_f32_e32 v65, 0xbfb8aa3b, v54
	v_mul_f32_e32 v66, 0xbfb8aa3b, v59
	v_exp_f32_e32 v63, v63
	v_exp_f32_e32 v65, v65
	v_exp_f32_e32 v66, v66
	v_mul_f32_e32 v67, 0xbfb8aa3b, v55
	v_exp_f32_e32 v67, v67
	v_add_f32_e32 v60, 1.0, v60
	v_min_f32_e32 v60, 0x7149f2ca, v60
	v_min_f32_e32 v61, 0x7149f2ca, v61
	v_min_f32_e32 v62, 0x7149f2ca, v62
	v_add_f32_e32 v63, 1.0, v63
	v_add_f32_e32 v65, 1.0, v65
	v_add_f32_e32 v66, 1.0, v66
	v_min_f32_e32 v63, 0x7149f2ca, v63
	v_min_f32_e32 v65, 0x7149f2ca, v65
	v_min_f32_e32 v66, 0x7149f2ca, v66
	v_add_f32_e32 v67, 1.0, v67
	v_cvt_pk_bf16_f32 v60, v60, v61
	v_cvt_pk_bf16_f32 v61, v63, v66
	v_cvt_pk_bf16_f32 v62, v64, v62
	v_min_f32_e32 v67, 0x7149f2ca, v67
	v_cvt_pk_bf16_f32 v63, v65, v67
	s_nop 0
	s_add_u32 s88, s90, 0x12000
	s_addc_u32 s89, s91, 0
	global_store_dwordx4 v253, v[60:63], s[88:89] nt
	s_cbranch_execz .LBB0_397

.LBB0_403:
	v_mul_f32_e32 v53, 0xbfb8aa3b, v44
	v_exp_f32_e32 v53, v53
	v_mul_f32_e32 v54, 0xbfb8aa3b, v49
	v_mul_f32_e32 v55, 0xbfb8aa3b, v45
	v_exp_f32_e32 v54, v54
	v_exp_f32_e32 v55, v55
	v_mul_f32_e32 v52, 0xbfb8aa3b, v48
	v_add_f32_e32 v53, 1.0, v53
	v_exp_f32_e32 v52, v52
	v_min_f32_e32 v56, 0x7149f2ca, v53
	v_add_f32_e32 v53, 1.0, v54
	v_add_f32_e32 v54, 1.0, v55
	v_mul_f32_e32 v55, 0xbfb8aa3b, v50
	v_mul_f32_e32 v57, 0xbfb8aa3b, v46
	v_mul_f32_e32 v58, 0xbfb8aa3b, v51
	v_exp_f32_e32 v55, v55
	v_exp_f32_e32 v57, v57
	v_exp_f32_e32 v58, v58
	v_mul_f32_e32 v59, 0xbfb8aa3b, v47
	v_exp_f32_e32 v59, v59
	v_add_f32_e32 v52, 1.0, v52
	v_min_f32_e32 v52, 0x7149f2ca, v52
	v_min_f32_e32 v53, 0x7149f2ca, v53
	v_min_f32_e32 v54, 0x7149f2ca, v54
	v_add_f32_e32 v55, 1.0, v55
	v_add_f32_e32 v57, 1.0, v57
	v_add_f32_e32 v58, 1.0, v58
	v_min_f32_e32 v55, 0x7149f2ca, v55
	v_min_f32_e32 v57, 0x7149f2ca, v57
	v_min_f32_e32 v58, 0x7149f2ca, v58
	v_add_f32_e32 v59, 1.0, v59
	v_cvt_pk_bf16_f32 v52, v52, v53
	v_cvt_pk_bf16_f32 v53, v55, v58
	v_cvt_pk_bf16_f32 v54, v56, v54
	v_min_f32_e32 v59, 0x7149f2ca, v59
	v_cvt_pk_bf16_f32 v55, v57, v59
	s_nop 0
	s_mov_b64 s[2:3], 0
	s_add_u32 s88, s90, 0x14000
	s_addc_u32 s89, s91, 0
	global_store_dwordx4 v253, v[52:55], s[88:89] nt

.LBB0_413:
	v_mul_f32_e32 v45, 0xbfb8aa3b, v36
	v_exp_f32_e32 v45, v45
	v_mul_f32_e32 v46, 0xbfb8aa3b, v41
	v_mul_f32_e32 v47, 0xbfb8aa3b, v37
	v_exp_f32_e32 v46, v46
	v_exp_f32_e32 v47, v47
	v_mul_f32_e32 v44, 0xbfb8aa3b, v40
	v_add_f32_e32 v45, 1.0, v45
	v_exp_f32_e32 v44, v44
	v_min_f32_e32 v48, 0x7149f2ca, v45
	v_add_f32_e32 v45, 1.0, v46
	v_add_f32_e32 v46, 1.0, v47
	v_mul_f32_e32 v47, 0xbfb8aa3b, v42
	v_mul_f32_e32 v49, 0xbfb8aa3b, v38
	v_mul_f32_e32 v50, 0xbfb8aa3b, v43
	v_exp_f32_e32 v47, v47
	v_exp_f32_e32 v49, v49
	v_exp_f32_e32 v50, v50
	v_mul_f32_e32 v51, 0xbfb8aa3b, v39
	v_exp_f32_e32 v51, v51
	v_add_f32_e32 v44, 1.0, v44
	v_min_f32_e32 v44, 0x7149f2ca, v44
	v_min_f32_e32 v45, 0x7149f2ca, v45
	v_min_f32_e32 v46, 0x7149f2ca, v46
	v_add_f32_e32 v47, 1.0, v47
	v_add_f32_e32 v49, 1.0, v49
	v_add_f32_e32 v50, 1.0, v50
	v_min_f32_e32 v47, 0x7149f2ca, v47
	v_min_f32_e32 v49, 0x7149f2ca, v49
	v_min_f32_e32 v50, 0x7149f2ca, v50
	v_add_f32_e32 v51, 1.0, v51
	v_cvt_pk_bf16_f32 v44, v44, v45
	v_cvt_pk_bf16_f32 v45, v47, v50
	v_cvt_pk_bf16_f32 v46, v48, v46
	v_min_f32_e32 v51, 0x7149f2ca, v51
	v_cvt_pk_bf16_f32 v47, v49, v51
	s_nop 0
	s_add_u32 s88, s90, 0x16000
	s_addc_u32 s89, s91, 0
	global_store_dwordx4 v253, v[44:47], s[88:89] nt
	s_cbranch_execz .LBB0_409

.LBB0_415:
	v_mul_f32_e32 v37, 0xbfb8aa3b, v28
	v_exp_f32_e32 v37, v37
	v_mul_f32_e32 v38, 0xbfb8aa3b, v33
	v_mul_f32_e32 v39, 0xbfb8aa3b, v29
	v_exp_f32_e32 v38, v38
	v_exp_f32_e32 v39, v39
	v_mul_f32_e32 v36, 0xbfb8aa3b, v32
	v_add_f32_e32 v37, 1.0, v37
	v_exp_f32_e32 v36, v36
	v_min_f32_e32 v40, 0x7149f2ca, v37
	v_add_f32_e32 v37, 1.0, v38
	v_add_f32_e32 v38, 1.0, v39
	v_mul_f32_e32 v39, 0xbfb8aa3b, v34
	v_mul_f32_e32 v41, 0xbfb8aa3b, v30
	v_mul_f32_e32 v42, 0xbfb8aa3b, v35
	v_exp_f32_e32 v39, v39
	v_exp_f32_e32 v41, v41
	v_exp_f32_e32 v42, v42
	v_mul_f32_e32 v43, 0xbfb8aa3b, v31
	v_exp_f32_e32 v43, v43
	v_add_f32_e32 v36, 1.0, v36
	v_min_f32_e32 v36, 0x7149f2ca, v36
	v_min_f32_e32 v37, 0x7149f2ca, v37
	v_min_f32_e32 v38, 0x7149f2ca, v38
	v_add_f32_e32 v39, 1.0, v39
	v_add_f32_e32 v41, 1.0, v41
	v_add_f32_e32 v42, 1.0, v42
	v_min_f32_e32 v39, 0x7149f2ca, v39
	v_min_f32_e32 v41, 0x7149f2ca, v41
	v_min_f32_e32 v42, 0x7149f2ca, v42
	v_add_f32_e32 v43, 1.0, v43
	v_cvt_pk_bf16_f32 v36, v36, v37
	v_cvt_pk_bf16_f32 v37, v39, v42
	v_cvt_pk_bf16_f32 v38, v40, v38
	v_min_f32_e32 v43, 0x7149f2ca, v43
	v_cvt_pk_bf16_f32 v39, v41, v43
	s_nop 0
	s_mov_b64 s[2:3], 0
	s_add_u32 s88, s90, 0x18000
	s_addc_u32 s89, s91, 0
	global_store_dwordx4 v253, v[36:39], s[88:89] nt

.LBB0_425:
	v_mul_f32_e32 v29, 0xbfb8aa3b, v20
	v_exp_f32_e32 v29, v29
	v_mul_f32_e32 v30, 0xbfb8aa3b, v25
	v_mul_f32_e32 v31, 0xbfb8aa3b, v21
	v_exp_f32_e32 v30, v30
	v_exp_f32_e32 v31, v31
	v_mul_f32_e32 v28, 0xbfb8aa3b, v24
	v_add_f32_e32 v29, 1.0, v29
	v_exp_f32_e32 v28, v28
	v_min_f32_e32 v32, 0x7149f2ca, v29
	v_add_f32_e32 v29, 1.0, v30
	v_add_f32_e32 v30, 1.0, v31
	v_mul_f32_e32 v31, 0xbfb8aa3b, v26
	v_mul_f32_e32 v33, 0xbfb8aa3b, v22
	v_mul_f32_e32 v34, 0xbfb8aa3b, v27
	v_exp_f32_e32 v31, v31
	v_exp_f32_e32 v33, v33
	v_exp_f32_e32 v34, v34
	v_mul_f32_e32 v35, 0xbfb8aa3b, v23
	v_exp_f32_e32 v35, v35
	v_add_f32_e32 v28, 1.0, v28
	v_min_f32_e32 v28, 0x7149f2ca, v28
	v_min_f32_e32 v29, 0x7149f2ca, v29
	v_min_f32_e32 v30, 0x7149f2ca, v30
	v_add_f32_e32 v31, 1.0, v31
	v_add_f32_e32 v33, 1.0, v33
	v_add_f32_e32 v34, 1.0, v34
	v_min_f32_e32 v31, 0x7149f2ca, v31
	v_min_f32_e32 v33, 0x7149f2ca, v33
	v_min_f32_e32 v34, 0x7149f2ca, v34
	v_add_f32_e32 v35, 1.0, v35
	v_cvt_pk_bf16_f32 v28, v28, v29
	v_cvt_pk_bf16_f32 v29, v31, v34
	v_cvt_pk_bf16_f32 v30, v32, v30
	v_min_f32_e32 v35, 0x7149f2ca, v35
	v_cvt_pk_bf16_f32 v31, v33, v35
	s_nop 0
	s_add_u32 s88, s90, 0x1a000
	s_addc_u32 s89, s91, 0
	global_store_dwordx4 v253, v[28:31], s[88:89] nt
	s_cbranch_execz .LBB0_421

.LBB0_427:
	v_mul_f32_e32 v21, 0xbfb8aa3b, v12
	v_exp_f32_e32 v21, v21
	v_mul_f32_e32 v22, 0xbfb8aa3b, v17
	v_mul_f32_e32 v23, 0xbfb8aa3b, v13
	v_exp_f32_e32 v22, v22
	v_exp_f32_e32 v23, v23
	v_mul_f32_e32 v20, 0xbfb8aa3b, v16
	v_add_f32_e32 v21, 1.0, v21
	v_exp_f32_e32 v20, v20
	v_min_f32_e32 v24, 0x7149f2ca, v21
	v_add_f32_e32 v21, 1.0, v22
	v_add_f32_e32 v22, 1.0, v23
	v_mul_f32_e32 v23, 0xbfb8aa3b, v18
	v_mul_f32_e32 v25, 0xbfb8aa3b, v14
	v_mul_f32_e32 v26, 0xbfb8aa3b, v19
	v_exp_f32_e32 v23, v23
	v_exp_f32_e32 v25, v25
	v_exp_f32_e32 v26, v26
	v_mul_f32_e32 v27, 0xbfb8aa3b, v15
	v_exp_f32_e32 v27, v27
	v_add_f32_e32 v20, 1.0, v20
	v_min_f32_e32 v20, 0x7149f2ca, v20
	v_min_f32_e32 v21, 0x7149f2ca, v21
	v_min_f32_e32 v22, 0x7149f2ca, v22
	v_add_f32_e32 v23, 1.0, v23
	v_add_f32_e32 v25, 1.0, v25
	v_add_f32_e32 v26, 1.0, v26
	v_min_f32_e32 v23, 0x7149f2ca, v23
	v_min_f32_e32 v25, 0x7149f2ca, v25
	v_min_f32_e32 v26, 0x7149f2ca, v26
	v_add_f32_e32 v27, 1.0, v27
	v_cvt_pk_bf16_f32 v20, v20, v21
	v_cvt_pk_bf16_f32 v21, v23, v26
	v_cvt_pk_bf16_f32 v22, v24, v22
	v_min_f32_e32 v27, 0x7149f2ca, v27
	v_cvt_pk_bf16_f32 v23, v25, v27
	s_nop 0
	s_mov_b64 s[2:3], 0
	s_add_u32 s88, s90, 0x1c000
	s_addc_u32 s89, s91, 0
	global_store_dwordx4 v253, v[20:23], s[88:89] nt

.LBB0_437:
	v_mul_f32_e32 v13, 0xbfb8aa3b, v4
	v_exp_f32_e32 v13, v13
	v_mul_f32_e32 v14, 0xbfb8aa3b, v9
	v_mul_f32_e32 v15, 0xbfb8aa3b, v5
	v_exp_f32_e32 v14, v14
	v_exp_f32_e32 v15, v15
	v_mul_f32_e32 v12, 0xbfb8aa3b, v8
	v_add_f32_e32 v13, 1.0, v13
	v_exp_f32_e32 v12, v12
	v_min_f32_e32 v16, 0x7149f2ca, v13
	v_add_f32_e32 v13, 1.0, v14
	v_add_f32_e32 v14, 1.0, v15
	v_mul_f32_e32 v15, 0xbfb8aa3b, v10
	v_mul_f32_e32 v17, 0xbfb8aa3b, v6
	v_mul_f32_e32 v18, 0xbfb8aa3b, v11
	v_exp_f32_e32 v15, v15
	v_exp_f32_e32 v17, v17
	v_exp_f32_e32 v18, v18
	v_mul_f32_e32 v19, 0xbfb8aa3b, v7
	v_exp_f32_e32 v19, v19
	v_add_f32_e32 v12, 1.0, v12
	v_min_f32_e32 v12, 0x7149f2ca, v12
	v_min_f32_e32 v13, 0x7149f2ca, v13
	v_min_f32_e32 v14, 0x7149f2ca, v14
	v_add_f32_e32 v15, 1.0, v15
	v_add_f32_e32 v17, 1.0, v17
	v_add_f32_e32 v18, 1.0, v18
	v_min_f32_e32 v15, 0x7149f2ca, v15
	v_min_f32_e32 v17, 0x7149f2ca, v17
	v_min_f32_e32 v18, 0x7149f2ca, v18
	v_add_f32_e32 v19, 1.0, v19
	v_cvt_pk_bf16_f32 v12, v12, v13
	v_cvt_pk_bf16_f32 v13, v15, v18
	v_cvt_pk_bf16_f32 v14, v16, v14
	v_min_f32_e32 v19, 0x7149f2ca, v19
	v_cvt_pk_bf16_f32 v15, v17, v19
	s_nop 0
	s_add_u32 s88, s90, 0x1e000
	s_addc_u32 s89, s91, 0
	global_store_dwordx4 v253, v[12:15], s[88:89] nt
	s_cbranch_execz .LBB0_433
